# select phase: expert ids and gates of four ranks stored as one 16-byte store each instead of one 4-byte store per rank
# speedup vs baseline: 1.0138x; 1.0014x over previous
; DI unsigned ordf(float f) { const unsigned u = __builtin_bit_cast(unsigned, f); return (u & 0x80000000u) ? ~u : (u | 0x80000000u); }
; DI void phase_peer_select(const Args& a, int layer, LAS unsigned char* lds) {
;     ...
;         unsigned ck[16][16];
; #pragma unroll
;         for (int x = 0; x < 16; ++x)
; #pragma unroll
;             for (int y = 0; y < 16; ++y)
;                 if ((x + 1) * (y + 1) <= 16) ck[x][y] = (ordf(unordf(t1[x] & ~0x7Fu) + unordf(t2[y] & ~0x7Fu)) & ~0xFFu) | (unsigned)(255 - (x * 16 + y));
;         const float scmax = unordf(ck[0][0] & ~0xFFu);
;         int* ip = IDX + m * 128 + h * 16; float* gp = GATE + m * 128 + h * 16;
;         float sum = 0.f;
; #pragma unroll 1
;         for (int k = 0; k < 16; ++k) {
;             unsigned mx = 0u;
; #pragma unroll
;             for (int x = 0; x < 16; ++x)
; #pragma unroll
;                 for (int y = 0; y < 16; ++y)
;                     if ((x + 1) * (y + 1) <= 16) mx = mx > ck[x][y] ? mx : ck[x][y];
; #pragma unroll
;             for (int x = 0; x < 16; ++x)
; #pragma unroll
;                 for (int y = 0; y < 16; ++y)
;                     if ((x + 1) * (y + 1) <= 16) ck[x][y] = ck[x][y] == mx ? 0u : ck[x][y];
.LBB0_46:
	v_mov_b32_e32 v150, 0
	v_mov_b32_e32 v151, 0
	v_mov_b32_e32 v154, 0
	v_mov_b32_e32 v155, 0
	v_mov_b32_e32 v158, 0
	v_mov_b32_e32 v159, 0
	v_mov_b32_e32 v160, 0
	v_mov_b32_e32 v161, 0
	v_mov_b32_e32 v166, 0
	v_mov_b32_e32 v167, 0
	v_mov_b32_e32 v171, 0
	v_mov_b32_e32 v173, 0
	v_mov_b32_e32 v177, 0
	v_mov_b32_e32 v178, 0
	v_max_u32_e32 v182, v49, v119
	v_min_u32_e32 v49, v49, v119
	v_max_u32_e32 v183, v13, v12
	v_min_u32_e32 v13, v13, v12
	v_max_u32_e32 v184, v39, v38
	v_min_u32_e32 v39, v39, v38
	v_max_u32_e32 v189, v19, v18
	v_min_u32_e32 v19, v19, v18
	v_max_u32_e32 v119, v31, v30
	v_min_u32_e32 v31, v31, v30
	v_max_u32_e32 v12, v35, v34
	v_min_u32_e32 v35, v35, v34
	v_max_u32_e32 v38, v41, v40
	v_min_u32_e32 v41, v41, v40
	v_max_u32_e32 v18, v150, v151
	v_min_u32_e32 v150, v150, v151
	v_max_u32_e32 v30, v182, v119
	v_min_u32_e32 v182, v182, v119
	v_max_u32_e32 v34, v183, v12
	v_min_u32_e32 v183, v183, v12
	v_max_u32_e32 v40, v184, v38
	v_min_u32_e32 v184, v184, v38
	v_max_u32_e32 v151, v189, v18
	v_min_u32_e32 v189, v189, v18
	v_max_u32_e32 v119, v49, v31
	v_min_u32_e32 v49, v49, v31
	v_max_u32_e32 v12, v13, v35
	v_min_u32_e32 v13, v13, v35
	v_max_u32_e32 v38, v39, v41
	v_min_u32_e32 v39, v39, v41
	v_max_u32_e32 v18, v19, v150
	v_min_u32_e32 v19, v19, v150
	v_max_u32_e32 v31, v119, v182
	v_min_u32_e32 v119, v119, v182
	v_max_u32_e32 v35, v12, v183
	v_min_u32_e32 v12, v12, v183
	v_max_u32_e32 v41, v38, v184
	v_min_u32_e32 v38, v38, v184
	v_max_u32_e32 v150, v18, v189
	v_min_u32_e32 v18, v18, v189
	v_max_u32_e32 v182, v17, v16
	v_min_u32_e32 v17, v17, v16
	v_max_u32_e32 v183, v21, v20
	v_min_u32_e32 v21, v21, v20
	v_max_u32_e32 v184, v43, v42
	v_min_u32_e32 v43, v43, v42
	v_max_u32_e32 v189, v154, v155
	v_min_u32_e32 v154, v154, v155
	v_max_u32_e32 v16, v9, v8
	v_min_u32_e32 v9, v9, v8
	v_max_u32_e32 v20, v11, v10
	v_min_u32_e32 v11, v11, v10
	v_max_u32_e32 v42, v45, v44
	v_min_u32_e32 v45, v45, v44
	v_max_u32_e32 v155, v158, v159
	v_min_u32_e32 v158, v158, v159
	v_max_u32_e32 v8, v182, v16
	v_min_u32_e32 v182, v182, v16
	v_max_u32_e32 v10, v183, v20
	v_min_u32_e32 v183, v183, v20
	v_max_u32_e32 v44, v184, v42
	v_min_u32_e32 v184, v184, v42
	v_max_u32_e32 v159, v189, v155
	v_min_u32_e32 v189, v189, v155
	v_max_u32_e32 v16, v17, v9
	v_min_u32_e32 v17, v17, v9
	v_max_u32_e32 v20, v21, v11
	v_min_u32_e32 v21, v21, v11
	v_max_u32_e32 v42, v43, v45
	v_min_u32_e32 v43, v43, v45
	v_max_u32_e32 v155, v154, v158
	v_min_u32_e32 v154, v154, v158
	v_max_u32_e32 v9, v16, v182
	v_min_u32_e32 v16, v16, v182
	v_max_u32_e32 v11, v20, v183
	v_min_u32_e32 v20, v20, v183
	v_max_u32_e32 v45, v42, v184
	v_min_u32_e32 v42, v42, v184
	v_max_u32_e32 v158, v155, v189
	v_min_u32_e32 v155, v155, v189
	v_max_u32_e32 v182, v30, v8
	v_min_u32_e32 v30, v30, v8
	v_max_u32_e32 v183, v34, v10
	v_min_u32_e32 v34, v34, v10
	v_max_u32_e32 v184, v40, v44
	v_min_u32_e32 v40, v40, v44
	v_max_u32_e32 v189, v151, v159
	v_min_u32_e32 v151, v151, v159
	v_max_u32_e32 v8, v119, v16
	v_min_u32_e32 v119, v119, v16
	v_max_u32_e32 v10, v12, v20
	v_min_u32_e32 v12, v12, v20
	v_max_u32_e32 v44, v38, v42
	v_min_u32_e32 v38, v38, v42
	v_max_u32_e32 v159, v18, v155
	v_min_u32_e32 v18, v18, v155
	v_max_u32_e32 v16, v8, v30
	v_min_u32_e32 v8, v8, v30
	v_max_u32_e32 v20, v10, v34
	v_min_u32_e32 v10, v10, v34
	v_max_u32_e32 v42, v44, v40
	v_min_u32_e32 v44, v44, v40
	v_max_u32_e32 v155, v159, v151
	v_min_u32_e32 v159, v159, v151
	v_max_u32_e32 v30, v31, v9
	v_min_u32_e32 v31, v31, v9
	v_max_u32_e32 v34, v35, v11
	v_min_u32_e32 v35, v35, v11
	v_max_u32_e32 v40, v41, v45
	v_min_u32_e32 v41, v41, v45
	v_max_u32_e32 v151, v150, v158
	v_min_u32_e32 v150, v150, v158
	v_max_u32_e32 v9, v49, v17
	v_min_u32_e32 v49, v49, v17
	v_max_u32_e32 v11, v13, v21
	v_min_u32_e32 v13, v13, v21
	v_max_u32_e32 v45, v39, v43
	v_min_u32_e32 v39, v39, v43
	v_max_u32_e32 v158, v19, v154
	v_min_u32_e32 v19, v19, v154
	v_max_u32_e32 v17, v9, v31
	v_min_u32_e32 v9, v9, v31
	v_max_u32_e32 v21, v11, v35
	v_min_u32_e32 v11, v11, v35
	v_max_u32_e32 v43, v45, v41
	v_min_u32_e32 v45, v45, v41
	v_max_u32_e32 v154, v158, v150
	v_min_u32_e32 v158, v158, v150
	v_max_u32_e32 v31, v30, v16
	v_min_u32_e32 v30, v30, v16
	v_max_u32_e32 v35, v34, v20
	v_min_u32_e32 v34, v34, v20
	v_max_u32_e32 v41, v40, v42
	v_min_u32_e32 v40, v40, v42
	v_max_u32_e32 v150, v151, v155
	v_min_u32_e32 v151, v151, v155
	v_max_u32_e32 v16, v17, v8
	v_min_u32_e32 v17, v17, v8
	v_max_u32_e32 v20, v21, v10
	v_min_u32_e32 v21, v21, v10
	v_max_u32_e32 v42, v43, v44
	v_min_u32_e32 v43, v43, v44
	v_max_u32_e32 v155, v154, v159
	v_min_u32_e32 v154, v154, v159
	v_max_u32_e32 v8, v9, v119
	v_min_u32_e32 v9, v9, v119
	v_max_u32_e32 v10, v11, v12
	v_min_u32_e32 v11, v11, v12
	v_max_u32_e32 v44, v45, v38
	v_min_u32_e32 v45, v45, v38
	v_max_u32_e32 v159, v158, v18
	v_min_u32_e32 v158, v158, v18
	v_max_u32_e32 v119, v1, v0
	v_min_u32_e32 v1, v1, v0
	v_max_u32_e32 v12, v15, v14
	v_min_u32_e32 v15, v15, v14
	v_max_u32_e32 v38, v47, v46
	v_min_u32_e32 v47, v47, v46
	v_max_u32_e32 v18, v160, v161
	v_min_u32_e32 v160, v160, v161
	v_max_u32_e32 v0, v3, v2
	v_min_u32_e32 v3, v3, v2
	v_max_u32_e32 v14, v37, v36
	v_min_u32_e32 v37, v37, v36
	v_max_u32_e32 v46, v33, v32
	v_min_u32_e32 v33, v33, v32
	v_max_u32_e32 v161, v166, v167
	v_min_u32_e32 v166, v166, v167
	v_max_u32_e32 v2, v119, v0
	v_min_u32_e32 v119, v119, v0
	v_max_u32_e32 v36, v12, v14
	v_min_u32_e32 v12, v12, v14
	v_max_u32_e32 v32, v38, v46
	v_min_u32_e32 v38, v38, v46
	v_max_u32_e32 v167, v18, v161
	v_min_u32_e32 v18, v18, v161
	v_max_u32_e32 v0, v1, v3
	v_min_u32_e32 v1, v1, v3
	v_max_u32_e32 v14, v15, v37
; DI void phase_peer_select(const Args& a, int layer, LAS unsigned char* lds) {
;     ...
;         for (int k = 0; k < 16; ++k) {
;             unsigned mx = 0u;
; #pragma unroll
;             for (int x = 0; x < 16; ++x)
; #pragma unroll
;                 for (int y = 0; y < 16; ++y)
;                     if ((x + 1) * (y + 1) <= 16) mx = mx > ck[x][y] ? mx : ck[x][y];
; #pragma unroll
;             for (int x = 0; x < 16; ++x)
; #pragma unroll
;                 for (int y = 0; y < 16; ++y)
;                     if ((x + 1) * (y + 1) <= 16) ck[x][y] = ck[x][y] == mx ? 0u : ck[x][y];
	v_min_u32_e32 v15, v15, v37
	v_max_u32_e32 v46, v47, v33
	v_min_u32_e32 v47, v47, v33
	v_max_u32_e32 v161, v160, v166
	v_min_u32_e32 v160, v160, v166
	v_max_u32_e32 v3, v0, v119
	v_min_u32_e32 v0, v0, v119
	v_max_u32_e32 v37, v14, v12
	v_min_u32_e32 v14, v14, v12
	v_max_u32_e32 v33, v46, v38
	v_min_u32_e32 v46, v46, v38
	v_max_u32_e32 v166, v161, v18
	v_min_u32_e32 v161, v161, v18
	v_max_u32_e32 v119, v5, v4
	v_min_u32_e32 v5, v5, v4
	v_max_u32_e32 v12, v25, v24
	v_min_u32_e32 v25, v25, v24
	v_max_u32_e32 v38, v29, v28
	v_min_u32_e32 v29, v29, v28
	v_max_u32_e32 v18, v171, v173
	v_min_u32_e32 v171, v171, v173
	v_max_u32_e32 v4, v7, v6
	v_min_u32_e32 v7, v7, v6
	v_max_u32_e32 v24, v27, v26
	v_min_u32_e32 v27, v27, v26
	v_max_u32_e32 v28, v23, v22
	v_min_u32_e32 v23, v23, v22
	v_max_u32_e32 v173, v177, v178
	v_min_u32_e32 v177, v177, v178
	v_max_u32_e32 v6, v119, v4
	v_min_u32_e32 v119, v119, v4
	v_max_u32_e32 v26, v12, v24
	v_min_u32_e32 v12, v12, v24
	v_max_u32_e32 v22, v38, v28
	v_min_u32_e32 v38, v38, v28
	v_max_u32_e32 v178, v18, v173
	v_min_u32_e32 v18, v18, v173
	v_max_u32_e32 v4, v5, v7
	v_min_u32_e32 v5, v5, v7
	v_max_u32_e32 v24, v25, v27
	v_min_u32_e32 v25, v25, v27
	v_max_u32_e32 v28, v29, v23
	v_min_u32_e32 v29, v29, v23
	v_max_u32_e32 v173, v171, v177
	v_min_u32_e32 v171, v171, v177
	v_max_u32_e32 v7, v4, v119
	v_min_u32_e32 v4, v4, v119
	v_max_u32_e32 v27, v24, v12
	v_min_u32_e32 v24, v24, v12
	v_max_u32_e32 v23, v28, v38
	v_min_u32_e32 v28, v28, v38
	v_max_u32_e32 v177, v173, v18
	v_min_u32_e32 v173, v173, v18
	v_max_u32_e32 v119, v2, v6
	v_min_u32_e32 v2, v2, v6
	v_max_u32_e32 v12, v36, v26
	v_min_u32_e32 v36, v36, v26
	v_max_u32_e32 v38, v32, v22
	v_min_u32_e32 v32, v32, v22
	v_max_u32_e32 v18, v167, v178
	v_min_u32_e32 v167, v167, v178
	v_max_u32_e32 v6, v0, v4
	v_min_u32_e32 v0, v0, v4
	v_max_u32_e32 v26, v14, v24
	v_min_u32_e32 v14, v14, v24
	v_max_u32_e32 v22, v46, v28
	v_min_u32_e32 v46, v46, v28
	v_max_u32_e32 v178, v161, v173
	v_min_u32_e32 v161, v161, v173
	v_max_u32_e32 v4, v6, v2
	v_min_u32_e32 v6, v6, v2
	v_max_u32_e32 v24, v26, v36
	v_min_u32_e32 v26, v26, v36
	v_max_u32_e32 v28, v22, v32
	v_min_u32_e32 v22, v22, v32
	v_max_u32_e32 v173, v178, v167
	v_min_u32_e32 v178, v178, v167
	v_max_u32_e32 v2, v3, v7
	v_min_u32_e32 v3, v3, v7
	v_max_u32_e32 v36, v37, v27
	v_min_u32_e32 v37, v37, v27
	v_max_u32_e32 v32, v33, v23
	v_min_u32_e32 v33, v33, v23
	v_max_u32_e32 v167, v166, v177
	v_min_u32_e32 v166, v166, v177
	v_max_u32_e32 v7, v1, v5
	v_min_u32_e32 v1, v1, v5
	v_max_u32_e32 v27, v15, v25
	v_min_u32_e32 v15, v15, v25
	v_max_u32_e32 v23, v47, v29
	v_min_u32_e32 v47, v47, v29
	v_max_u32_e32 v177, v160, v171
	v_min_u32_e32 v160, v160, v171
	v_max_u32_e32 v5, v7, v3
	v_min_u32_e32 v7, v7, v3
	v_max_u32_e32 v25, v27, v37
	v_min_u32_e32 v27, v27, v37
	v_max_u32_e32 v29, v23, v33
	v_min_u32_e32 v23, v23, v33
	v_max_u32_e32 v171, v177, v166
	v_min_u32_e32 v177, v177, v166
	v_max_u32_e32 v3, v2, v4
	v_min_u32_e32 v2, v2, v4
	v_max_u32_e32 v37, v36, v24
	v_min_u32_e32 v36, v36, v24
	v_max_u32_e32 v33, v32, v28
	v_min_u32_e32 v32, v32, v28
	v_max_u32_e32 v166, v167, v173
	v_min_u32_e32 v167, v167, v173
	v_max_u32_e32 v4, v5, v6
	v_min_u32_e32 v5, v5, v6
	v_max_u32_e32 v24, v25, v26
	v_min_u32_e32 v25, v25, v26
	v_max_u32_e32 v28, v29, v22
	v_min_u32_e32 v29, v29, v22
	v_max_u32_e32 v173, v171, v178
	v_min_u32_e32 v171, v171, v178
	v_max_u32_e32 v6, v7, v0
	v_min_u32_e32 v7, v7, v0
	v_max_u32_e32 v26, v27, v14
	v_min_u32_e32 v27, v27, v14
	v_max_u32_e32 v22, v23, v46
	v_min_u32_e32 v23, v23, v46
	v_max_u32_e32 v178, v177, v161
	v_min_u32_e32 v177, v177, v161
	v_max_u32_e32 v0, v182, v119
	v_min_u32_e32 v182, v182, v119
	v_max_u32_e32 v14, v183, v12
	v_min_u32_e32 v183, v183, v12
	v_max_u32_e32 v46, v184, v38
	v_min_u32_e32 v184, v184, v38
	v_max_u32_e32 v161, v189, v18
	v_min_u32_e32 v189, v189, v18
	v_max_u32_e32 v119, v17, v5
	v_min_u32_e32 v17, v17, v5
	v_max_u32_e32 v12, v21, v25
	v_min_u32_e32 v21, v21, v25
	v_max_u32_e32 v38, v43, v29
	v_min_u32_e32 v43, v43, v29
	v_max_u32_e32 v18, v154, v171
	v_min_u32_e32 v154, v154, v171
	v_max_u32_e32 v5, v119, v182
	v_min_u32_e32 v119, v119, v182
	v_max_u32_e32 v25, v12, v183
	v_min_u32_e32 v12, v12, v183
	v_max_u32_e32 v29, v38, v184
	v_min_u32_e32 v38, v38, v184
	v_max_u32_e32 v171, v18, v189
	v_min_u32_e32 v18, v18, v189
	v_max_u32_e32 v182, v30, v2
	v_min_u32_e32 v30, v30, v2
	v_max_u32_e32 v183, v34, v36
	v_min_u32_e32 v34, v34, v36
	v_max_u32_e32 v184, v40, v32
	v_min_u32_e32 v40, v40, v32
	v_max_u32_e32 v189, v151, v167
	v_min_u32_e32 v151, v151, v167
	v_max_u32_e32 v2, v9, v7
	v_min_u32_e32 v9, v9, v7
	v_max_u32_e32 v36, v11, v27
	v_min_u32_e32 v11, v11, v27
	v_max_u32_e32 v32, v45, v23
	v_min_u32_e32 v45, v45, v23
	v_max_u32_e32 v167, v158, v177
	v_min_u32_e32 v158, v158, v177
	v_max_u32_e32 v7, v2, v30
	v_min_u32_e32 v2, v2, v30
	v_max_u32_e32 v27, v36, v34
	v_min_u32_e32 v36, v36, v34
	v_max_u32_e32 v23, v32, v40
	v_min_u32_e32 v32, v32, v40
	v_max_u32_e32 v177, v167, v151
	v_min_u32_e32 v167, v167, v151
	v_max_u32_e32 v30, v182, v5
	v_min_u32_e32 v182, v182, v5
	v_max_u32_e32 v34, v183, v25
	v_min_u32_e32 v183, v183, v25
	v_max_u32_e32 v40, v184, v29
	v_min_u32_e32 v184, v184, v29
	v_max_u32_e32 v151, v189, v171
	v_min_u32_e32 v189, v189, v171
	v_max_u32_e32 v5, v7, v119
	v_min_u32_e32 v7, v7, v119
	v_max_u32_e32 v25, v27, v12
	v_min_u32_e32 v27, v27, v12
	v_max_u32_e32 v29, v23, v38
	v_min_u32_e32 v23, v23, v38
	v_max_u32_e32 v171, v177, v18
	v_min_u32_e32 v177, v177, v18
	v_max_u32_e32 v119, v2, v17
	v_min_u32_e32 v2, v2, v17
	v_max_u32_e32 v12, v36, v21
; DI void phase_peer_select(const Args& a, int layer, LAS unsigned char* lds) {
;     ...
;         for (int k = 0; k < 16; ++k) {
;             unsigned mx = 0u;
; #pragma unroll
;             for (int x = 0; x < 16; ++x)
; #pragma unroll
;                 for (int y = 0; y < 16; ++y)
;                     if ((x + 1) * (y + 1) <= 16) mx = mx > ck[x][y] ? mx : ck[x][y];
; #pragma unroll
;             for (int x = 0; x < 16; ++x)
; #pragma unroll
;                 for (int y = 0; y < 16; ++y)
;                     if ((x + 1) * (y + 1) <= 16) ck[x][y] = ck[x][y] == mx ? 0u : ck[x][y];
	v_min_u32_e32 v36, v36, v21
	v_max_u32_e32 v38, v32, v43
	v_min_u32_e32 v32, v32, v43
	v_max_u32_e32 v18, v167, v154
	v_min_u32_e32 v167, v167, v154
	v_max_u32_e32 v17, v31, v3
	v_min_u32_e32 v31, v31, v3
	v_max_u32_e32 v21, v35, v37
	v_min_u32_e32 v35, v35, v37
	v_max_u32_e32 v43, v41, v33
	v_min_u32_e32 v41, v41, v33
	v_max_u32_e32 v154, v150, v166
	v_min_u32_e32 v150, v150, v166
	v_max_u32_e32 v3, v8, v6
	v_min_u32_e32 v8, v8, v6
	v_max_u32_e32 v37, v10, v26
	v_min_u32_e32 v10, v10, v26
	v_max_u32_e32 v33, v44, v22
	v_min_u32_e32 v44, v44, v22
	v_max_u32_e32 v166, v159, v178
	v_min_u32_e32 v159, v159, v178
	v_max_u32_e32 v6, v3, v31
	v_min_u32_e32 v3, v3, v31
	v_max_u32_e32 v26, v37, v35
	v_min_u32_e32 v37, v37, v35
	v_max_u32_e32 v22, v33, v41
	v_min_u32_e32 v33, v33, v41
	v_max_u32_e32 v178, v166, v150
	v_min_u32_e32 v166, v166, v150
	v_max_u32_e32 v31, v16, v4
	v_min_u32_e32 v16, v16, v4
	v_max_u32_e32 v35, v20, v24
	v_min_u32_e32 v20, v20, v24
	v_max_u32_e32 v41, v42, v28
	v_min_u32_e32 v42, v42, v28
	v_max_u32_e32 v150, v155, v173
	v_min_u32_e32 v155, v155, v173
	v_max_u32_e32 v4, v49, v1
	v_min_u32_e32 v49, v49, v1
	v_max_u32_e32 v24, v13, v15
	v_min_u32_e32 v13, v13, v15
	v_max_u32_e32 v28, v39, v47
	v_min_u32_e32 v39, v39, v47
	v_max_u32_e32 v173, v19, v160
	v_min_u32_e32 v19, v19, v160
	v_max_u32_e32 v1, v4, v16
	v_min_u32_e32 v4, v4, v16
	v_max_u32_e32 v15, v24, v20
	v_min_u32_e32 v24, v24, v20
	v_max_u32_e32 v47, v28, v42
	v_min_u32_e32 v28, v28, v42
	v_max_u32_e32 v160, v173, v155
	v_min_u32_e32 v173, v173, v155
	v_max_u32_e32 v16, v31, v6
	v_min_u32_e32 v31, v31, v6
	v_max_u32_e32 v20, v35, v26
	v_min_u32_e32 v35, v35, v26
	v_max_u32_e32 v42, v41, v22
	v_min_u32_e32 v41, v41, v22
	v_max_u32_e32 v155, v150, v178
	v_min_u32_e32 v150, v150, v178
	v_max_u32_e32 v6, v1, v3
	v_min_u32_e32 v1, v1, v3
	v_max_u32_e32 v26, v15, v37
	v_min_u32_e32 v15, v15, v37
	v_max_u32_e32 v22, v47, v33
	v_min_u32_e32 v47, v47, v33
	v_max_u32_e32 v178, v160, v166
	v_min_u32_e32 v160, v160, v166
	v_max_u32_e32 v3, v4, v8
	v_min_u32_e32 v4, v4, v8
	v_max_u32_e32 v37, v24, v10
	v_min_u32_e32 v24, v24, v10
	v_max_u32_e32 v33, v28, v44
	v_min_u32_e32 v28, v28, v44
	v_max_u32_e32 v166, v173, v159
	v_min_u32_e32 v173, v173, v159
	v_max_u32_e32 v8, v17, v30
	v_min_u32_e32 v17, v17, v30
	v_max_u32_e32 v10, v21, v34
	v_min_u32_e32 v21, v21, v34
	v_max_u32_e32 v44, v43, v40
	v_min_u32_e32 v43, v43, v40
	v_max_u32_e32 v159, v154, v151
	v_min_u32_e32 v154, v154, v151
	v_max_u32_e32 v30, v16, v182
	v_min_u32_e32 v16, v16, v182
	v_max_u32_e32 v34, v20, v183
	v_min_u32_e32 v20, v20, v183
	v_max_u32_e32 v40, v42, v184
	v_min_u32_e32 v42, v42, v184
	v_max_u32_e32 v151, v155, v189
	v_min_u32_e32 v155, v155, v189
	v_max_u32_e32 v182, v31, v5
	v_min_u32_e32 v31, v31, v5
	v_max_u32_e32 v183, v35, v25
	v_min_u32_e32 v35, v35, v25
	v_max_u32_e32 v184, v41, v29
	v_min_u32_e32 v41, v41, v29
	v_max_u32_e32 v189, v150, v171
	v_min_u32_e32 v150, v150, v171
	v_max_u32_e32 v5, v6, v7
	v_min_u32_e32 v6, v6, v7
	v_max_u32_e32 v25, v26, v27
	v_min_u32_e32 v26, v26, v27
	v_max_u32_e32 v29, v22, v23
	v_min_u32_e32 v22, v22, v23
	v_max_u32_e32 v171, v178, v177
	v_min_u32_e32 v178, v178, v177
	v_max_u32_e32 v7, v1, v119
	v_min_u32_e32 v1, v1, v119
	v_max_u32_e32 v27, v15, v12
	v_min_u32_e32 v15, v15, v12
	v_max_u32_e32 v23, v47, v38
	v_min_u32_e32 v47, v47, v38
	v_max_u32_e32 v177, v160, v18
	v_min_u32_e32 v160, v160, v18
	v_max_u32_e32 v119, v3, v2
	v_min_u32_e32 v3, v3, v2
	v_max_u32_e32 v12, v37, v36
	v_min_u32_e32 v37, v37, v36
	v_max_u32_e32 v38, v33, v32
	v_min_u32_e32 v33, v33, v32
	v_max_u32_e32 v18, v166, v167
	v_min_u32_e32 v166, v166, v167
	v_max_u32_e32 v2, v4, v9
	v_min_u32_e32 v4, v4, v9
	v_max_u32_e32 v36, v24, v11
	v_min_u32_e32 v24, v24, v11
	v_max_u32_e32 v32, v28, v45
	v_min_u32_e32 v28, v28, v45
	v_max_u32_e32 v167, v173, v158
	v_min_u32_e32 v173, v173, v158
	v_max_u32_e32 v0, v0, v13
	v_max_u32_e32 v46, v46, v19
	v_max_u32_e32 v8, v8, v24
	v_max_u32_e32 v44, v44, v173
	v_max_u32_e32 v17, v17, v36
	v_max_u32_e32 v43, v43, v167
	v_max_u32_e32 v30, v30, v37
	v_max_u32_e32 v40, v40, v166
	v_max_u32_e32 v16, v16, v12
	v_max_u32_e32 v42, v42, v18
	v_max_u32_e32 v182, v182, v15
	v_max_u32_e32 v184, v184, v160
	v_max_u32_e32 v31, v31, v27
	v_max_u32_e32 v41, v41, v177
	v_max_u32_e32 v5, v5, v26
	v_max_u32_e32 v29, v29, v178
	v_max_u32_e32 v6, v6, v25
	v_max_u32_e32 v22, v22, v171
	v_max_u32_e32 v7, v7, v35
	v_max_u32_e32 v23, v23, v150
	v_max_u32_e32 v1, v1, v183
	v_max_u32_e32 v47, v47, v189
	v_max_u32_e32 v119, v119, v20
	v_max_u32_e32 v38, v38, v155
	v_max_u32_e32 v3, v3, v34
	v_max_u32_e32 v33, v33, v151
	v_max_u32_e32 v2, v2, v21
	v_max_u32_e32 v32, v32, v154
	v_max_u32_e32 v4, v4, v10
	v_max_u32_e32 v28, v28, v159
	v_max_u32_e32 v49, v49, v14
	v_max_u32_e32 v39, v39, v161
	v_max_u32_e32 v9, v0, v6
	v_min_u32_e32 v0, v0, v6
	v_max_u32_e32 v45, v46, v22
	v_min_u32_e32 v46, v46, v22
	v_max_u32_e32 v6, v8, v7
	v_min_u32_e32 v8, v8, v7
	v_max_u32_e32 v22, v44, v23
	v_min_u32_e32 v44, v44, v23
	v_max_u32_e32 v7, v17, v1
	v_min_u32_e32 v17, v17, v1
	v_max_u32_e32 v23, v43, v47
	v_min_u32_e32 v43, v43, v47
	v_max_u32_e32 v1, v30, v119
	v_min_u32_e32 v30, v30, v119
	v_max_u32_e32 v47, v40, v38
	v_min_u32_e32 v40, v40, v38
	v_max_u32_e32 v119, v16, v3
	v_min_u32_e32 v16, v16, v3
	v_max_u32_e32 v38, v42, v33
	v_min_u32_e32 v42, v42, v33
	v_max_u32_e32 v3, v182, v2
	v_min_u32_e32 v182, v182, v2
	v_max_u32_e32 v33, v184, v32
	v_min_u32_e32 v184, v184, v32
	v_max_u32_e32 v2, v31, v4
	v_min_u32_e32 v31, v31, v4
	v_max_u32_e32 v32, v41, v28
	v_min_u32_e32 v41, v41, v28
; DI void phase_peer_select(const Args& a, int layer, LAS unsigned char* lds) {
;     ...
;         for (int k = 0; k < 16; ++k) {
;             unsigned mx = 0u;
; #pragma unroll
;             for (int x = 0; x < 16; ++x)
; #pragma unroll
;                 for (int y = 0; y < 16; ++y)
;                     if ((x + 1) * (y + 1) <= 16) mx = mx > ck[x][y] ? mx : ck[x][y];
; #pragma unroll
;             for (int x = 0; x < 16; ++x)
; #pragma unroll
;                 for (int y = 0; y < 16; ++y)
;                     if ((x + 1) * (y + 1) <= 16) ck[x][y] = ck[x][y] == mx ? 0u : ck[x][y];
;             const int ci = 255 - (int)(mx & 0xFFu);
;             const int e = (int)(127u - (lt1[(ci >> 4) * 64 + lane] & 0x7Fu)) * 128 + (int)(127u - (lt2[(ci & 15) * 64 + lane] & 0x7Fu));
;             const float ek = __expf(unordf(mx & ~0xFFu) - scmax);
;             sum += ek;
;             if (hi == 0) { ip[k] = e; gp[k] = ek; }
	v_max_u32_e32 v4, v5, v49
	v_min_u32_e32 v5, v5, v49
	v_max_u32_e32 v28, v29, v39
	v_min_u32_e32 v29, v29, v39
	v_max_u32_e32 v49, v9, v119
	v_min_u32_e32 v9, v9, v119
	v_max_u32_e32 v39, v45, v38
	v_min_u32_e32 v45, v45, v38
	v_max_u32_e32 v119, v6, v3
	v_min_u32_e32 v6, v6, v3
	v_max_u32_e32 v38, v22, v33
	v_min_u32_e32 v22, v22, v33
	v_max_u32_e32 v3, v7, v2
	v_min_u32_e32 v7, v7, v2
	v_max_u32_e32 v33, v23, v32
	v_min_u32_e32 v23, v23, v32
	v_max_u32_e32 v2, v1, v4
	v_min_u32_e32 v1, v1, v4
	v_max_u32_e32 v32, v47, v28
	v_min_u32_e32 v47, v47, v28
	v_max_u32_e32 v4, v0, v16
	v_min_u32_e32 v0, v0, v16
	v_max_u32_e32 v28, v46, v42
	v_min_u32_e32 v46, v46, v42
	v_max_u32_e32 v16, v8, v182
	v_min_u32_e32 v8, v8, v182
	v_max_u32_e32 v42, v44, v184
	v_min_u32_e32 v44, v44, v184
	v_max_u32_e32 v182, v17, v31
	v_min_u32_e32 v17, v17, v31
	v_max_u32_e32 v184, v43, v41
	v_min_u32_e32 v43, v43, v41
	v_max_u32_e32 v31, v30, v5
	v_min_u32_e32 v30, v30, v5
	v_max_u32_e32 v41, v40, v29
	v_min_u32_e32 v40, v40, v29
	v_max_u32_e32 v5, v49, v3
	v_min_u32_e32 v49, v49, v3
	v_max_u32_e32 v29, v39, v33
	v_min_u32_e32 v39, v39, v33
	v_max_u32_e32 v3, v119, v2
	v_min_u32_e32 v119, v119, v2
	v_max_u32_e32 v33, v38, v32
	v_min_u32_e32 v38, v38, v32
	v_max_u32_e32 v2, v9, v7
	v_min_u32_e32 v9, v9, v7
	v_max_u32_e32 v32, v45, v23
	v_min_u32_e32 v45, v45, v23
	v_max_u32_e32 v7, v6, v1
	v_min_u32_e32 v6, v6, v1
	v_max_u32_e32 v23, v22, v47
	v_min_u32_e32 v22, v22, v47
	v_max_u32_e32 v1, v4, v182
	v_min_u32_e32 v4, v4, v182
	v_max_u32_e32 v47, v28, v184
	v_min_u32_e32 v28, v28, v184
	v_max_u32_e32 v182, v16, v31
	v_min_u32_e32 v16, v16, v31
	v_max_u32_e32 v184, v42, v41
	v_min_u32_e32 v42, v42, v41
	v_max_u32_e32 v31, v0, v17
	v_min_u32_e32 v0, v0, v17
	v_max_u32_e32 v41, v46, v43
	v_min_u32_e32 v46, v46, v43
	v_max_u32_e32 v17, v8, v30
	v_min_u32_e32 v8, v8, v30
	v_max_u32_e32 v43, v44, v40
	v_min_u32_e32 v44, v44, v40
	v_max_u32_e32 v30, v5, v3
	v_min_u32_e32 v5, v5, v3
	v_max_u32_e32 v40, v29, v33
	v_min_u32_e32 v29, v29, v33
	v_max_u32_e32 v3, v49, v119
	v_min_u32_e32 v49, v49, v119
	v_max_u32_e32 v33, v39, v38
	v_min_u32_e32 v39, v39, v38
	v_max_u32_e32 v119, v2, v7
	v_min_u32_e32 v2, v2, v7
	v_max_u32_e32 v38, v32, v23
	v_min_u32_e32 v32, v32, v23
	v_max_u32_e32 v7, v9, v6
	v_min_u32_e32 v9, v9, v6
	v_max_u32_e32 v23, v45, v22
	v_min_u32_e32 v45, v45, v22
	v_max_u32_e32 v6, v1, v182
	v_min_u32_e32 v1, v1, v182
	v_max_u32_e32 v22, v47, v184
	v_min_u32_e32 v47, v47, v184
	v_max_u32_e32 v182, v4, v16
	v_min_u32_e32 v4, v4, v16
	v_max_u32_e32 v184, v28, v42
	v_min_u32_e32 v28, v28, v42
	v_max_u32_e32 v16, v31, v17
	v_min_u32_e32 v31, v31, v17
	v_max_u32_e32 v42, v41, v43
	v_min_u32_e32 v41, v41, v43
	v_max_u32_e32 v17, v0, v8
	v_min_u32_e32 v0, v0, v8
	v_max_u32_e32 v43, v46, v44
	v_min_u32_e32 v46, v46, v44
	v_max_u32_e32 v30, v30, v46
	v_max_u32_e32 v5, v5, v43
	v_max_u32_e32 v3, v3, v41
	v_max_u32_e32 v49, v49, v42
	v_max_u32_e32 v119, v119, v28
	v_max_u32_e32 v2, v2, v184
	v_max_u32_e32 v7, v7, v47
	v_max_u32_e32 v9, v9, v22
	v_max_u32_e32 v6, v6, v45
	v_max_u32_e32 v1, v1, v23
	v_max_u32_e32 v182, v182, v32
	v_max_u32_e32 v4, v4, v38
	v_max_u32_e32 v16, v16, v39
	v_max_u32_e32 v31, v31, v33
	v_max_u32_e32 v17, v17, v29
	v_max_u32_e32 v0, v0, v40
	v_max_u32_e32 v8, v30, v6
	v_min_u32_e32 v30, v30, v6
	v_max_u32_e32 v6, v5, v1
	v_min_u32_e32 v5, v5, v1
	v_max_u32_e32 v1, v3, v182
	v_min_u32_e32 v3, v3, v182
	v_max_u32_e32 v182, v49, v4
	v_min_u32_e32 v49, v49, v4
	v_max_u32_e32 v4, v119, v16
	v_min_u32_e32 v119, v119, v16
	v_max_u32_e32 v16, v2, v31
	v_min_u32_e32 v2, v2, v31
	v_max_u32_e32 v31, v7, v17
	v_min_u32_e32 v7, v7, v17
	v_max_u32_e32 v17, v9, v0
	v_min_u32_e32 v9, v9, v0
	v_max_u32_e32 v0, v8, v4
	v_min_u32_e32 v8, v8, v4
	v_max_u32_e32 v4, v6, v16
	v_min_u32_e32 v6, v6, v16
	v_max_u32_e32 v16, v1, v31
	v_min_u32_e32 v1, v1, v31
	v_max_u32_e32 v31, v182, v17
	v_min_u32_e32 v182, v182, v17
	v_max_u32_e32 v17, v30, v119
	v_min_u32_e32 v30, v30, v119
	v_max_u32_e32 v119, v5, v2
	v_min_u32_e32 v5, v5, v2
	v_max_u32_e32 v2, v3, v7
	v_min_u32_e32 v3, v3, v7
	v_max_u32_e32 v7, v49, v9
	v_min_u32_e32 v49, v49, v9
	v_max_u32_e32 v9, v0, v16
	v_min_u32_e32 v0, v0, v16
	v_max_u32_e32 v16, v4, v31
	v_min_u32_e32 v4, v4, v31
	v_max_u32_e32 v31, v8, v1
	v_min_u32_e32 v8, v8, v1
	v_max_u32_e32 v1, v6, v182
	v_min_u32_e32 v6, v6, v182
	v_max_u32_e32 v182, v17, v2
	v_min_u32_e32 v17, v17, v2
	v_max_u32_e32 v2, v119, v7
	v_min_u32_e32 v119, v119, v7
	v_max_u32_e32 v7, v30, v3
	v_min_u32_e32 v30, v30, v3
	v_max_u32_e32 v3, v5, v49
	v_min_u32_e32 v5, v5, v49
	v_max_u32_e32 v49, v9, v16
	v_min_u32_e32 v9, v9, v16
	v_max_u32_e32 v16, v0, v4
	v_min_u32_e32 v0, v0, v4
	v_max_u32_e32 v4, v31, v1
	v_min_u32_e32 v31, v31, v1
	v_max_u32_e32 v1, v8, v6
	v_min_u32_e32 v8, v8, v6
	v_max_u32_e32 v6, v182, v2
	v_min_u32_e32 v182, v182, v2
	v_max_u32_e32 v2, v17, v119
	v_min_u32_e32 v17, v17, v119
	v_max_u32_e32 v119, v7, v3
	v_min_u32_e32 v7, v7, v3
	v_max_u32_e32 v3, v30, v5
	v_min_u32_e32 v30, v30, v5
	s_movk_i32 s8, 0xff
	v_and_b32_e32 v141, 0x7fffff00, v49
	v_bitop3_b32 v143, v49, s8, v49 bitop3:0xcf
	v_cmp_gt_i32_e32 vcc, 0, v49
	s_nop 1
	v_cndmask_b32_e32 v141, v143, v141, vcc
	v_sub_f32_e32 v141, v141, v131
	v_mul_f32_e32 v141, 0x3fb8aa3b, v141
	v_exp_f32_e32 v141, v141
	s_and_saveexec_b64 s[8:9], s[38:39]
	s_cbranch_execz .Lp_cand_0
	v_not_b32_e32 v143, v49
	v_lshlrev_b32_e32 v144, 8, v143
	v_lshlrev_b32_e32 v143, 4, v143
	v_and_b32_e32 v144, 0xf00, v144
	v_and_b32_e32 v143, 0xf00, v143
	v_add_u32_e32 v144, v216, v144
	v_add_u32_e32 v143, v216, v143
	ds_read_b32 v146, v144 offset:4096
	ds_read_b32 v143, v143
	s_movk_i32 s16, 0x3fff
	s_waitcnt lgkmcnt(1)
	v_and_b32_e32 v146, 0x7f, v146
	s_waitcnt lgkmcnt(0)
	v_lshlrev_b32_e32 v143, 7, v143
	v_and_b32_e32 v143, 0x3f80, v143
	v_bitop3_b32 v143, v143, s16, v146 bitop3:0x36
	v_mov_b32_e32 v220, v143
	v_mov_b32_e32 v236, v141
; DI void phase_peer_select(const Args& a, int layer, LAS unsigned char* lds) {
;     ...
;         for (int k = 0; k < 16; ++k) {
;             unsigned mx = 0u;
; #pragma unroll
;             for (int x = 0; x < 16; ++x)
; #pragma unroll
;                 for (int y = 0; y < 16; ++y)
;                     if ((x + 1) * (y + 1) <= 16) mx = mx > ck[x][y] ? mx : ck[x][y];
; #pragma unroll
;             for (int x = 0; x < 16; ++x)
; #pragma unroll
;                 for (int y = 0; y < 16; ++y)
;                     if ((x + 1) * (y + 1) <= 16) ck[x][y] = ck[x][y] == mx ? 0u : ck[x][y];
;             const int ci = 255 - (int)(mx & 0xFFu);
;             const int e = (int)(127u - (lt1[(ci >> 4) * 64 + lane] & 0x7Fu)) * 128 + (int)(127u - (lt2[(ci & 15) * 64 + lane] & 0x7Fu));
;             const float ek = __expf(unordf(mx & ~0xFFu) - scmax);
;             sum += ek;
;             if (hi == 0) { ip[k] = e; gp[k] = ek; }
.Lp_cand_0:
	s_or_b64 exec, exec, s[8:9]
	s_add_u32 s0, s0, 4
	s_addc_u32 s1, s1, 0
	v_add_f32_e32 v128, v128, v141
	s_movk_i32 s8, 0xff
	v_and_b32_e32 v141, 0x7fffff00, v9
	v_bitop3_b32 v143, v9, s8, v9 bitop3:0xcf
	v_cmp_gt_i32_e32 vcc, 0, v9
	s_nop 1
	v_cndmask_b32_e32 v141, v143, v141, vcc
	v_sub_f32_e32 v141, v141, v131
	v_mul_f32_e32 v141, 0x3fb8aa3b, v141
	v_exp_f32_e32 v141, v141
	s_and_saveexec_b64 s[8:9], s[38:39]
	s_cbranch_execz .Lp_cand_1
	v_not_b32_e32 v143, v9
	v_lshlrev_b32_e32 v144, 8, v143
	v_lshlrev_b32_e32 v143, 4, v143
	v_and_b32_e32 v144, 0xf00, v144
	v_and_b32_e32 v143, 0xf00, v143
	v_add_u32_e32 v144, v216, v144
	v_add_u32_e32 v143, v216, v143
	ds_read_b32 v146, v144 offset:4096
	ds_read_b32 v143, v143
	s_movk_i32 s16, 0x3fff
	s_waitcnt lgkmcnt(1)
	v_and_b32_e32 v146, 0x7f, v146
	s_waitcnt lgkmcnt(0)
	v_lshlrev_b32_e32 v143, 7, v143
	v_and_b32_e32 v143, 0x3f80, v143
	v_bitop3_b32 v143, v143, s16, v146 bitop3:0x36
	v_mov_b32_e32 v221, v143
	v_mov_b32_e32 v237, v141
.Lp_cand_1:
	s_or_b64 exec, exec, s[8:9]
	s_add_u32 s0, s0, 4
	s_addc_u32 s1, s1, 0
	v_add_f32_e32 v128, v128, v141
	s_movk_i32 s8, 0xff
	v_and_b32_e32 v141, 0x7fffff00, v16
	v_bitop3_b32 v143, v16, s8, v16 bitop3:0xcf
	v_cmp_gt_i32_e32 vcc, 0, v16
	s_nop 1
	v_cndmask_b32_e32 v141, v143, v141, vcc
	v_sub_f32_e32 v141, v141, v131
	v_mul_f32_e32 v141, 0x3fb8aa3b, v141
	v_exp_f32_e32 v141, v141
	s_and_saveexec_b64 s[8:9], s[38:39]
	s_cbranch_execz .Lp_cand_2
	v_not_b32_e32 v143, v16
	v_lshlrev_b32_e32 v144, 8, v143
	v_lshlrev_b32_e32 v143, 4, v143
	v_and_b32_e32 v144, 0xf00, v144
	v_and_b32_e32 v143, 0xf00, v143
	v_add_u32_e32 v144, v216, v144
	v_add_u32_e32 v143, v216, v143
	ds_read_b32 v146, v144 offset:4096
	ds_read_b32 v143, v143
	s_movk_i32 s16, 0x3fff
	s_waitcnt lgkmcnt(1)
	v_and_b32_e32 v146, 0x7f, v146
	s_waitcnt lgkmcnt(0)
	v_lshlrev_b32_e32 v143, 7, v143
	v_and_b32_e32 v143, 0x3f80, v143
	v_bitop3_b32 v143, v143, s16, v146 bitop3:0x36
	v_mov_b32_e32 v222, v143
	v_mov_b32_e32 v238, v141
.Lp_cand_2:
	s_or_b64 exec, exec, s[8:9]
	s_add_u32 s0, s0, 4
	s_addc_u32 s1, s1, 0
	v_add_f32_e32 v128, v128, v141
	s_movk_i32 s8, 0xff
	v_and_b32_e32 v141, 0x7fffff00, v0
	v_bitop3_b32 v143, v0, s8, v0 bitop3:0xcf
	v_cmp_gt_i32_e32 vcc, 0, v0
	s_nop 1
	v_cndmask_b32_e32 v141, v143, v141, vcc
	v_sub_f32_e32 v141, v141, v131
	v_mul_f32_e32 v141, 0x3fb8aa3b, v141
	v_exp_f32_e32 v141, v141
	s_and_saveexec_b64 s[8:9], s[38:39]
	s_cbranch_execz .Lp_cand_3
	v_not_b32_e32 v143, v0
	v_lshlrev_b32_e32 v144, 8, v143
	v_lshlrev_b32_e32 v143, 4, v143
	v_and_b32_e32 v144, 0xf00, v144
	v_and_b32_e32 v143, 0xf00, v143
	v_add_u32_e32 v144, v216, v144
	v_add_u32_e32 v143, v216, v143
	ds_read_b32 v146, v144 offset:4096
	ds_read_b32 v143, v143
	s_movk_i32 s16, 0x3fff
	s_waitcnt lgkmcnt(1)
	v_and_b32_e32 v146, 0x7f, v146
	s_waitcnt lgkmcnt(0)
	v_lshlrev_b32_e32 v143, 7, v143
	v_and_b32_e32 v143, 0x3f80, v143
	v_bitop3_b32 v143, v143, s16, v146 bitop3:0x36
	v_mov_b32_e32 v223, v143
	v_mov_b32_e32 v239, v141
	v_lshl_add_u64 v[144:145], v[124:125], 0, s[0:1]
	s_nop 0
	v_add_co_u32_e32 v146, vcc, 0x6000000, v144
	s_nop 1
	v_addc_co_u32_e32 v147, vcc, 0, v145, vcc
	v_add_co_u32_e32 v144, vcc, 0x7000000, v144
	s_nop 1
	v_addc_co_u32_e32 v145, vcc, 0, v145, vcc
	global_store_dwordx4 v[146:147], v[220:223], off offset:-12
	global_store_dwordx4 v[144:145], v[236:239], off offset:-12
.Lp_cand_3:
	s_or_b64 exec, exec, s[8:9]
	s_add_u32 s0, s0, 4
	s_addc_u32 s1, s1, 0
	v_add_f32_e32 v128, v128, v141
	s_movk_i32 s8, 0xff
	v_and_b32_e32 v141, 0x7fffff00, v4
	v_bitop3_b32 v143, v4, s8, v4 bitop3:0xcf
	v_cmp_gt_i32_e32 vcc, 0, v4
	s_nop 1
	v_cndmask_b32_e32 v141, v143, v141, vcc
	v_sub_f32_e32 v141, v141, v131
	v_mul_f32_e32 v141, 0x3fb8aa3b, v141
	v_exp_f32_e32 v141, v141
	s_and_saveexec_b64 s[8:9], s[38:39]
	s_cbranch_execz .Lp_cand_4
	v_not_b32_e32 v143, v4
	v_lshlrev_b32_e32 v144, 8, v143
	v_lshlrev_b32_e32 v143, 4, v143
	v_and_b32_e32 v144, 0xf00, v144
	v_and_b32_e32 v143, 0xf00, v143
	v_add_u32_e32 v144, v216, v144
	v_add_u32_e32 v143, v216, v143
	ds_read_b32 v146, v144 offset:4096
	ds_read_b32 v143, v143
	s_movk_i32 s16, 0x3fff
	s_waitcnt lgkmcnt(1)
	v_and_b32_e32 v146, 0x7f, v146
	s_waitcnt lgkmcnt(0)
	v_lshlrev_b32_e32 v143, 7, v143
	v_and_b32_e32 v143, 0x3f80, v143
	v_bitop3_b32 v143, v143, s16, v146 bitop3:0x36
	v_mov_b32_e32 v220, v143
	v_mov_b32_e32 v236, v141
.Lp_cand_4:
	s_or_b64 exec, exec, s[8:9]
	s_add_u32 s0, s0, 4
	s_addc_u32 s1, s1, 0
	v_add_f32_e32 v128, v128, v141
	s_movk_i32 s8, 0xff
	v_and_b32_e32 v141, 0x7fffff00, v31
	v_bitop3_b32 v143, v31, s8, v31 bitop3:0xcf
	v_cmp_gt_i32_e32 vcc, 0, v31
	s_nop 1
	v_cndmask_b32_e32 v141, v143, v141, vcc
	v_sub_f32_e32 v141, v141, v131
	v_mul_f32_e32 v141, 0x3fb8aa3b, v141
	v_exp_f32_e32 v141, v141
	s_and_saveexec_b64 s[8:9], s[38:39]
	s_cbranch_execz .Lp_cand_5
	v_not_b32_e32 v143, v31
	v_lshlrev_b32_e32 v144, 8, v143
	v_lshlrev_b32_e32 v143, 4, v143
	v_and_b32_e32 v144, 0xf00, v144
	v_and_b32_e32 v143, 0xf00, v143
	v_add_u32_e32 v144, v216, v144
	v_add_u32_e32 v143, v216, v143
	ds_read_b32 v146, v144 offset:4096
	ds_read_b32 v143, v143
	s_movk_i32 s16, 0x3fff
	s_waitcnt lgkmcnt(1)
	v_and_b32_e32 v146, 0x7f, v146
	s_waitcnt lgkmcnt(0)
	v_lshlrev_b32_e32 v143, 7, v143
	v_and_b32_e32 v143, 0x3f80, v143
	v_bitop3_b32 v143, v143, s16, v146 bitop3:0x36
	v_mov_b32_e32 v221, v143
	v_mov_b32_e32 v237, v141
; DI void phase_peer_select(const Args& a, int layer, LAS unsigned char* lds) {
;     ...
;         for (int k = 0; k < 16; ++k) {
;             unsigned mx = 0u;
; #pragma unroll
;             for (int x = 0; x < 16; ++x)
; #pragma unroll
;                 for (int y = 0; y < 16; ++y)
;                     if ((x + 1) * (y + 1) <= 16) mx = mx > ck[x][y] ? mx : ck[x][y];
; #pragma unroll
;             for (int x = 0; x < 16; ++x)
; #pragma unroll
;                 for (int y = 0; y < 16; ++y)
;                     if ((x + 1) * (y + 1) <= 16) ck[x][y] = ck[x][y] == mx ? 0u : ck[x][y];
;             const int ci = 255 - (int)(mx & 0xFFu);
;             const int e = (int)(127u - (lt1[(ci >> 4) * 64 + lane] & 0x7Fu)) * 128 + (int)(127u - (lt2[(ci & 15) * 64 + lane] & 0x7Fu));
;             const float ek = __expf(unordf(mx & ~0xFFu) - scmax);
;             sum += ek;
;             if (hi == 0) { ip[k] = e; gp[k] = ek; }
;         }
.Lp_cand_5:
	s_or_b64 exec, exec, s[8:9]
	s_add_u32 s0, s0, 4
	s_addc_u32 s1, s1, 0
	v_add_f32_e32 v128, v128, v141
	s_movk_i32 s8, 0xff
	v_and_b32_e32 v141, 0x7fffff00, v1
	v_bitop3_b32 v143, v1, s8, v1 bitop3:0xcf
	v_cmp_gt_i32_e32 vcc, 0, v1
	s_nop 1
	v_cndmask_b32_e32 v141, v143, v141, vcc
	v_sub_f32_e32 v141, v141, v131
	v_mul_f32_e32 v141, 0x3fb8aa3b, v141
	v_exp_f32_e32 v141, v141
	s_and_saveexec_b64 s[8:9], s[38:39]
	s_cbranch_execz .Lp_cand_6
	v_not_b32_e32 v143, v1
	v_lshlrev_b32_e32 v144, 8, v143
	v_lshlrev_b32_e32 v143, 4, v143
	v_and_b32_e32 v144, 0xf00, v144
	v_and_b32_e32 v143, 0xf00, v143
	v_add_u32_e32 v144, v216, v144
	v_add_u32_e32 v143, v216, v143
	ds_read_b32 v146, v144 offset:4096
	ds_read_b32 v143, v143
	s_movk_i32 s16, 0x3fff
	s_waitcnt lgkmcnt(1)
	v_and_b32_e32 v146, 0x7f, v146
	s_waitcnt lgkmcnt(0)
	v_lshlrev_b32_e32 v143, 7, v143
	v_and_b32_e32 v143, 0x3f80, v143
	v_bitop3_b32 v143, v143, s16, v146 bitop3:0x36
	v_mov_b32_e32 v222, v143
	v_mov_b32_e32 v238, v141
.Lp_cand_6:
	s_or_b64 exec, exec, s[8:9]
	s_add_u32 s0, s0, 4
	s_addc_u32 s1, s1, 0
	v_add_f32_e32 v128, v128, v141
	s_movk_i32 s8, 0xff
	v_and_b32_e32 v141, 0x7fffff00, v8
	v_bitop3_b32 v143, v8, s8, v8 bitop3:0xcf
	v_cmp_gt_i32_e32 vcc, 0, v8
	s_nop 1
	v_cndmask_b32_e32 v141, v143, v141, vcc
	v_sub_f32_e32 v141, v141, v131
	v_mul_f32_e32 v141, 0x3fb8aa3b, v141
	v_exp_f32_e32 v141, v141
	s_and_saveexec_b64 s[8:9], s[38:39]
	s_cbranch_execz .Lp_cand_7
	v_not_b32_e32 v143, v8
	v_lshlrev_b32_e32 v144, 8, v143
	v_lshlrev_b32_e32 v143, 4, v143
	v_and_b32_e32 v144, 0xf00, v144
	v_and_b32_e32 v143, 0xf00, v143
	v_add_u32_e32 v144, v216, v144
	v_add_u32_e32 v143, v216, v143
	ds_read_b32 v146, v144 offset:4096
	ds_read_b32 v143, v143
	s_movk_i32 s16, 0x3fff
	s_waitcnt lgkmcnt(1)
	v_and_b32_e32 v146, 0x7f, v146
	s_waitcnt lgkmcnt(0)
	v_lshlrev_b32_e32 v143, 7, v143
	v_and_b32_e32 v143, 0x3f80, v143
	v_bitop3_b32 v143, v143, s16, v146 bitop3:0x36
	v_mov_b32_e32 v223, v143
	v_mov_b32_e32 v239, v141
	v_lshl_add_u64 v[144:145], v[124:125], 0, s[0:1]
	s_nop 0
	v_add_co_u32_e32 v146, vcc, 0x6000000, v144
	s_nop 1
	v_addc_co_u32_e32 v147, vcc, 0, v145, vcc
	v_add_co_u32_e32 v144, vcc, 0x7000000, v144
	s_nop 1
	v_addc_co_u32_e32 v145, vcc, 0, v145, vcc
	global_store_dwordx4 v[146:147], v[220:223], off offset:-12
	global_store_dwordx4 v[144:145], v[236:239], off offset:-12
.Lp_cand_7:
	s_or_b64 exec, exec, s[8:9]
	s_add_u32 s0, s0, 4
	s_addc_u32 s1, s1, 0
	v_add_f32_e32 v128, v128, v141
	s_movk_i32 s8, 0xff
	v_and_b32_e32 v141, 0x7fffff00, v6
	v_bitop3_b32 v143, v6, s8, v6 bitop3:0xcf
	v_cmp_gt_i32_e32 vcc, 0, v6
	s_nop 1
	v_cndmask_b32_e32 v141, v143, v141, vcc
	v_sub_f32_e32 v141, v141, v131
	v_mul_f32_e32 v141, 0x3fb8aa3b, v141
	v_exp_f32_e32 v141, v141
	s_and_saveexec_b64 s[8:9], s[38:39]
	s_cbranch_execz .Lp_cand_8
	v_not_b32_e32 v143, v6
	v_lshlrev_b32_e32 v144, 8, v143
	v_lshlrev_b32_e32 v143, 4, v143
	v_and_b32_e32 v144, 0xf00, v144
	v_and_b32_e32 v143, 0xf00, v143
	v_add_u32_e32 v144, v216, v144
	v_add_u32_e32 v143, v216, v143
	ds_read_b32 v146, v144 offset:4096
	ds_read_b32 v143, v143
	s_movk_i32 s16, 0x3fff
	s_waitcnt lgkmcnt(1)
	v_and_b32_e32 v146, 0x7f, v146
	s_waitcnt lgkmcnt(0)
	v_lshlrev_b32_e32 v143, 7, v143
	v_and_b32_e32 v143, 0x3f80, v143
	v_bitop3_b32 v143, v143, s16, v146 bitop3:0x36
	v_mov_b32_e32 v220, v143
	v_mov_b32_e32 v236, v141
.Lp_cand_8:
	s_or_b64 exec, exec, s[8:9]
	s_add_u32 s0, s0, 4
	s_addc_u32 s1, s1, 0
	v_add_f32_e32 v128, v128, v141
	s_movk_i32 s8, 0xff
	v_and_b32_e32 v141, 0x7fffff00, v182
	v_bitop3_b32 v143, v182, s8, v182 bitop3:0xcf
	v_cmp_gt_i32_e32 vcc, 0, v182
	s_nop 1
	v_cndmask_b32_e32 v141, v143, v141, vcc
	v_sub_f32_e32 v141, v141, v131
	v_mul_f32_e32 v141, 0x3fb8aa3b, v141
	v_exp_f32_e32 v141, v141
	s_and_saveexec_b64 s[8:9], s[38:39]
	s_cbranch_execz .Lp_cand_9
	v_not_b32_e32 v143, v182
	v_lshlrev_b32_e32 v144, 8, v143
	v_lshlrev_b32_e32 v143, 4, v143
	v_and_b32_e32 v144, 0xf00, v144
	v_and_b32_e32 v143, 0xf00, v143
	v_add_u32_e32 v144, v216, v144
	v_add_u32_e32 v143, v216, v143
	ds_read_b32 v146, v144 offset:4096
	ds_read_b32 v143, v143
	s_movk_i32 s16, 0x3fff
	s_waitcnt lgkmcnt(1)
	v_and_b32_e32 v146, 0x7f, v146
	s_waitcnt lgkmcnt(0)
	v_lshlrev_b32_e32 v143, 7, v143
	v_and_b32_e32 v143, 0x3f80, v143
	v_bitop3_b32 v143, v143, s16, v146 bitop3:0x36
	v_mov_b32_e32 v221, v143
	v_mov_b32_e32 v237, v141
.Lp_cand_9:
	s_or_b64 exec, exec, s[8:9]
	s_add_u32 s0, s0, 4
	s_addc_u32 s1, s1, 0
	v_add_f32_e32 v128, v128, v141
	s_movk_i32 s8, 0xff
	v_and_b32_e32 v141, 0x7fffff00, v2
	v_bitop3_b32 v143, v2, s8, v2 bitop3:0xcf
	v_cmp_gt_i32_e32 vcc, 0, v2
	s_nop 1
	v_cndmask_b32_e32 v141, v143, v141, vcc
	v_sub_f32_e32 v141, v141, v131
	v_mul_f32_e32 v141, 0x3fb8aa3b, v141
	v_exp_f32_e32 v141, v141
	s_and_saveexec_b64 s[8:9], s[38:39]
	s_cbranch_execz .Lp_cand_10
	v_not_b32_e32 v143, v2
	v_lshlrev_b32_e32 v144, 8, v143
	v_lshlrev_b32_e32 v143, 4, v143
	v_and_b32_e32 v144, 0xf00, v144
	v_and_b32_e32 v143, 0xf00, v143
	v_add_u32_e32 v144, v216, v144
	v_add_u32_e32 v143, v216, v143
	ds_read_b32 v146, v144 offset:4096
	ds_read_b32 v143, v143
	s_movk_i32 s16, 0x3fff
	s_waitcnt lgkmcnt(1)
	v_and_b32_e32 v146, 0x7f, v146
	s_waitcnt lgkmcnt(0)
	v_lshlrev_b32_e32 v143, 7, v143
	v_and_b32_e32 v143, 0x3f80, v143
	v_bitop3_b32 v143, v143, s16, v146 bitop3:0x36
	v_mov_b32_e32 v222, v143
	v_mov_b32_e32 v238, v141
; DI void phase_peer_select(const Args& a, int layer, LAS unsigned char* lds) {
;     ...
;         for (int k = 0; k < 16; ++k) {
;             unsigned mx = 0u;
; #pragma unroll
;             for (int x = 0; x < 16; ++x)
; #pragma unroll
;                 for (int y = 0; y < 16; ++y)
;                     if ((x + 1) * (y + 1) <= 16) mx = mx > ck[x][y] ? mx : ck[x][y];
; #pragma unroll
;             for (int x = 0; x < 16; ++x)
; #pragma unroll
;                 for (int y = 0; y < 16; ++y)
;                     if ((x + 1) * (y + 1) <= 16) ck[x][y] = ck[x][y] == mx ? 0u : ck[x][y];
;             const int ci = 255 - (int)(mx & 0xFFu);
;             const int e = (int)(127u - (lt1[(ci >> 4) * 64 + lane] & 0x7Fu)) * 128 + (int)(127u - (lt2[(ci & 15) * 64 + lane] & 0x7Fu));
;             const float ek = __expf(unordf(mx & ~0xFFu) - scmax);
;             sum += ek;
;             if (hi == 0) { ip[k] = e; gp[k] = ek; }
;         }
.Lp_cand_10:
	s_or_b64 exec, exec, s[8:9]
	s_add_u32 s0, s0, 4
	s_addc_u32 s1, s1, 0
	v_add_f32_e32 v128, v128, v141
	s_movk_i32 s8, 0xff
	v_and_b32_e32 v141, 0x7fffff00, v17
	v_bitop3_b32 v143, v17, s8, v17 bitop3:0xcf
	v_cmp_gt_i32_e32 vcc, 0, v17
	s_nop 1
	v_cndmask_b32_e32 v141, v143, v141, vcc
	v_sub_f32_e32 v141, v141, v131
	v_mul_f32_e32 v141, 0x3fb8aa3b, v141
	v_exp_f32_e32 v141, v141
	s_and_saveexec_b64 s[8:9], s[38:39]
	s_cbranch_execz .Lp_cand_11
	v_not_b32_e32 v143, v17
	v_lshlrev_b32_e32 v144, 8, v143
	v_lshlrev_b32_e32 v143, 4, v143
	v_and_b32_e32 v144, 0xf00, v144
	v_and_b32_e32 v143, 0xf00, v143
	v_add_u32_e32 v144, v216, v144
	v_add_u32_e32 v143, v216, v143
	ds_read_b32 v146, v144 offset:4096
	ds_read_b32 v143, v143
	s_movk_i32 s16, 0x3fff
	s_waitcnt lgkmcnt(1)
	v_and_b32_e32 v146, 0x7f, v146
	s_waitcnt lgkmcnt(0)
	v_lshlrev_b32_e32 v143, 7, v143
	v_and_b32_e32 v143, 0x3f80, v143
	v_bitop3_b32 v143, v143, s16, v146 bitop3:0x36
	v_mov_b32_e32 v223, v143
	v_mov_b32_e32 v239, v141
	v_lshl_add_u64 v[144:145], v[124:125], 0, s[0:1]
	s_nop 0
	v_add_co_u32_e32 v146, vcc, 0x6000000, v144
	s_nop 1
	v_addc_co_u32_e32 v147, vcc, 0, v145, vcc
	v_add_co_u32_e32 v144, vcc, 0x7000000, v144
	s_nop 1
	v_addc_co_u32_e32 v145, vcc, 0, v145, vcc
	global_store_dwordx4 v[146:147], v[220:223], off offset:-12
	global_store_dwordx4 v[144:145], v[236:239], off offset:-12
.Lp_cand_11:
	s_or_b64 exec, exec, s[8:9]
	s_add_u32 s0, s0, 4
	s_addc_u32 s1, s1, 0
	v_add_f32_e32 v128, v128, v141
	s_movk_i32 s8, 0xff
	v_and_b32_e32 v141, 0x7fffff00, v119
	v_bitop3_b32 v143, v119, s8, v119 bitop3:0xcf
	v_cmp_gt_i32_e32 vcc, 0, v119
	s_nop 1
	v_cndmask_b32_e32 v141, v143, v141, vcc
	v_sub_f32_e32 v141, v141, v131
	v_mul_f32_e32 v141, 0x3fb8aa3b, v141
	v_exp_f32_e32 v141, v141
	s_and_saveexec_b64 s[8:9], s[38:39]
	s_cbranch_execz .Lp_cand_12
	v_not_b32_e32 v143, v119
	v_lshlrev_b32_e32 v144, 8, v143
	v_lshlrev_b32_e32 v143, 4, v143
	v_and_b32_e32 v144, 0xf00, v144
	v_and_b32_e32 v143, 0xf00, v143
	v_add_u32_e32 v144, v216, v144
	v_add_u32_e32 v143, v216, v143
	ds_read_b32 v146, v144 offset:4096
	ds_read_b32 v143, v143
	s_movk_i32 s16, 0x3fff
	s_waitcnt lgkmcnt(1)
	v_and_b32_e32 v146, 0x7f, v146
	s_waitcnt lgkmcnt(0)
	v_lshlrev_b32_e32 v143, 7, v143
	v_and_b32_e32 v143, 0x3f80, v143
	v_bitop3_b32 v143, v143, s16, v146 bitop3:0x36
	v_mov_b32_e32 v220, v143
	v_mov_b32_e32 v236, v141
.Lp_cand_12:
	s_or_b64 exec, exec, s[8:9]
	s_add_u32 s0, s0, 4
	s_addc_u32 s1, s1, 0
	v_add_f32_e32 v128, v128, v141
	s_movk_i32 s8, 0xff
	v_and_b32_e32 v141, 0x7fffff00, v7
	v_bitop3_b32 v143, v7, s8, v7 bitop3:0xcf
	v_cmp_gt_i32_e32 vcc, 0, v7
	s_nop 1
	v_cndmask_b32_e32 v141, v143, v141, vcc
	v_sub_f32_e32 v141, v141, v131
	v_mul_f32_e32 v141, 0x3fb8aa3b, v141
	v_exp_f32_e32 v141, v141
	s_and_saveexec_b64 s[8:9], s[38:39]
	s_cbranch_execz .Lp_cand_13
	v_not_b32_e32 v143, v7
	v_lshlrev_b32_e32 v144, 8, v143
	v_lshlrev_b32_e32 v143, 4, v143
	v_and_b32_e32 v144, 0xf00, v144
	v_and_b32_e32 v143, 0xf00, v143
	v_add_u32_e32 v144, v216, v144
	v_add_u32_e32 v143, v216, v143
	ds_read_b32 v146, v144 offset:4096
	ds_read_b32 v143, v143
	s_movk_i32 s16, 0x3fff
	s_waitcnt lgkmcnt(1)
	v_and_b32_e32 v146, 0x7f, v146
	s_waitcnt lgkmcnt(0)
	v_lshlrev_b32_e32 v143, 7, v143
	v_and_b32_e32 v143, 0x3f80, v143
	v_bitop3_b32 v143, v143, s16, v146 bitop3:0x36
	v_mov_b32_e32 v221, v143
	v_mov_b32_e32 v237, v141
.Lp_cand_13:
	s_or_b64 exec, exec, s[8:9]
	s_add_u32 s0, s0, 4
	s_addc_u32 s1, s1, 0
	v_add_f32_e32 v128, v128, v141
	s_movk_i32 s8, 0xff
	v_and_b32_e32 v141, 0x7fffff00, v3
	v_bitop3_b32 v143, v3, s8, v3 bitop3:0xcf
	v_cmp_gt_i32_e32 vcc, 0, v3
	s_nop 1
	v_cndmask_b32_e32 v141, v143, v141, vcc
	v_sub_f32_e32 v141, v141, v131
	v_mul_f32_e32 v141, 0x3fb8aa3b, v141
	v_exp_f32_e32 v141, v141
	s_and_saveexec_b64 s[8:9], s[38:39]
	s_cbranch_execz .Lp_cand_14
	v_not_b32_e32 v143, v3
	v_lshlrev_b32_e32 v144, 8, v143
	v_lshlrev_b32_e32 v143, 4, v143
	v_and_b32_e32 v144, 0xf00, v144
	v_and_b32_e32 v143, 0xf00, v143
	v_add_u32_e32 v144, v216, v144
	v_add_u32_e32 v143, v216, v143
	ds_read_b32 v146, v144 offset:4096
	ds_read_b32 v143, v143
	s_movk_i32 s16, 0x3fff
	s_waitcnt lgkmcnt(1)
	v_and_b32_e32 v146, 0x7f, v146
	s_waitcnt lgkmcnt(0)
	v_lshlrev_b32_e32 v143, 7, v143
	v_and_b32_e32 v143, 0x3f80, v143
	v_bitop3_b32 v143, v143, s16, v146 bitop3:0x36
	v_mov_b32_e32 v222, v143
	v_mov_b32_e32 v238, v141
.Lp_cand_14:
	s_or_b64 exec, exec, s[8:9]
	s_add_u32 s0, s0, 4
	s_addc_u32 s1, s1, 0
	v_add_f32_e32 v128, v128, v141
	s_movk_i32 s8, 0xff
	v_and_b32_e32 v141, 0x7fffff00, v30
	v_bitop3_b32 v143, v30, s8, v30 bitop3:0xcf
	v_cmp_gt_i32_e32 vcc, 0, v30
	s_nop 1
	v_cndmask_b32_e32 v141, v143, v141, vcc
	v_sub_f32_e32 v141, v141, v131
	v_mul_f32_e32 v141, 0x3fb8aa3b, v141
	v_exp_f32_e32 v141, v141
	s_and_saveexec_b64 s[8:9], s[38:39]
	s_cbranch_execz .Lp_cand_15
	v_not_b32_e32 v143, v30
	v_lshlrev_b32_e32 v144, 8, v143
	v_lshlrev_b32_e32 v143, 4, v143
	v_and_b32_e32 v144, 0xf00, v144
	v_and_b32_e32 v143, 0xf00, v143
	v_add_u32_e32 v144, v216, v144
	v_add_u32_e32 v143, v216, v143
	ds_read_b32 v146, v144 offset:4096
	ds_read_b32 v143, v143
	s_movk_i32 s16, 0x3fff
	s_waitcnt lgkmcnt(1)
	v_and_b32_e32 v146, 0x7f, v146
	s_waitcnt lgkmcnt(0)
	v_lshlrev_b32_e32 v143, 7, v143
	v_and_b32_e32 v143, 0x3f80, v143
	v_bitop3_b32 v143, v143, s16, v146 bitop3:0x36
	v_mov_b32_e32 v223, v143
	v_mov_b32_e32 v239, v141
	v_lshl_add_u64 v[144:145], v[124:125], 0, s[0:1]
	s_nop 0
	v_add_co_u32_e32 v146, vcc, 0x6000000, v144
	s_nop 1
	v_addc_co_u32_e32 v147, vcc, 0, v145, vcc
	v_add_co_u32_e32 v144, vcc, 0x7000000, v144
	s_nop 1
	v_addc_co_u32_e32 v145, vcc, 0, v145, vcc
	global_store_dwordx4 v[146:147], v[220:223], off offset:-12
	global_store_dwordx4 v[144:145], v[236:239], off offset:-12
